# plus: static s_setprio 1 for waves 4-7 inside the two hand-written steady attention loops
# speedup vs baseline: 1.0021x; 1.0021x over previous
.Lfox_nockp:
	s_or_b64 exec, exec, s[12:13]
	global_load_dwordx4 v[118:121], v[248:249], off
	s_mov_b64 s[14:15], 0x10000
	v_lshl_add_u64 v[242:243], v[244:245], 0, s[14:15]
	v_lshl_add_u64 v[244:245], v[242:243], 0, s[14:15]
	v_lshl_add_u64 v[246:247], v[248:249], 0, s[14:15]
	v_lshl_add_u64 v[248:249], v[246:247], 0, s[14:15]
	s_mov_b64 s[14:15], 0x100
	v_lshl_add_u64 v[250:251], v[250:251], 0, s[14:15]
	ds_read_b128 v[78:81], v158 offset:43264
	ds_read_b128 v[82:85], v158 offset:43296
	ds_read_b128 v[86:89], v158 offset:43328
	ds_read_b128 v[90:93], v158 offset:43360
	ds_read_b128 v[94:97], v158 offset:43392
	ds_read_b128 v[98:101], v158 offset:43424
	ds_read_b128 v[102:105], v158 offset:43456
	ds_read_b128 v[106:109], v158 offset:43488
	s_waitcnt lgkmcnt(4)
	ds_read_b128 v[190:193], v218 offset:13312
	ds_read_b128 v[194:197], v218 offset:17920
	ds_read_b128 v[198:201], v218 offset:13344
	ds_read_b128 v[202:205], v218 offset:17952
	ds_read_b128 v[206:209], v218 offset:13376
	ds_read_b128 v[210:213], v218 offset:17984
	ds_read_b128 v[214:217], v218 offset:13408
	ds_read_b128 v[222:225], v218 offset:18016
	v_max3_f32 v124, v46, v47, v48
	v_max3_f32 v125, v49, v50, v51
	v_max3_f32 v124, v124, v52, v53
	v_max3_f32 v125, v125, v54, v55
	v_max3_f32 v124, v124, v56, v57
	v_max3_f32 v125, v125, v58, v59
	v_max3_f32 v124, v124, v60, v61
	v_max3_f32 v125, v125, v62, v63
	v_max3_f32 v124, v124, v64, v65
	v_max3_f32 v125, v125, v66, v67
	v_max3_f32 v124, v124, v68, v69
	v_max3_f32 v125, v125, v70, v71
	v_max3_f32 v124, v124, v72, v73
	v_max3_f32 v125, v125, v74, v75
	v_max3_f32 v124, v124, v76, v77
	v_max_f32_e32 v124, v124, v125
	v_mov_b32_e32 v125, v124
	s_nop 1
	v_permlane32_swap_b32_e32 v124, v125
	v_max_f32_e32 v126, v124, v125
	s_cmp_ge_u32 s33, 4
	s_cbranch_scc0 .Lnoprio_f
	s_setprio 1
.Lnoprio_f:
.Lfox_loop:
	v_add_f32_e32 v127, 0x41800000, v160
	v_cmp_gt_f32_e32 vcc, v126, v127
	s_cbranch_vccnz .Lfox_resc0

.Lfox_nock1:
	s_or_b64 exec, exec, s[12:13]
	global_load_dwordx4 v[118:121], v[248:249], off
	v_max3_f32 v125, v125, v54, v55
	v_max3_f32 v124, v124, v56, v57
	v_max3_f32 v125, v125, v58, v59
	v_mfma_f32_32x32x16_bf16 v[14:29], v[198:201], v[230:233], v[14:29]
	ds_read_b128 v[198:201], v218 offset:13344
	v_max3_f32 v124, v124, v60, v61
	v_max3_f32 v125, v125, v62, v63
	v_max3_f32 v124, v124, v64, v65
	v_mfma_f32_32x32x16_bf16 v[30:45], v[202:205], v[230:233], v[30:45]
	ds_read_b128 v[202:205], v218 offset:17952
	v_max3_f32 v125, v125, v66, v67
	v_max3_f32 v124, v124, v68, v69
	v_max3_f32 v125, v125, v70, v71
	v_mfma_f32_32x32x16_bf16 v[14:29], v[206:209], v[234:237], v[14:29]
	ds_read_b128 v[206:209], v218 offset:13376
	v_max3_f32 v124, v124, v72, v73
	v_max3_f32 v125, v125, v74, v75
	v_mfma_f32_32x32x16_bf16 v[30:45], v[210:213], v[234:237], v[30:45]
	ds_read_b128 v[210:213], v218 offset:17984
	v_max3_f32 v124, v124, v76, v77
	v_max_f32_e32 v124, v124, v125
	v_mfma_f32_32x32x16_bf16 v[14:29], v[214:217], v[238:241], v[14:29]
	ds_read_b128 v[214:217], v218 offset:13408
	v_mov_b32_e32 v125, v124
	s_nop 1
	v_mfma_f32_32x32x16_bf16 v[30:45], v[222:225], v[238:241], v[30:45]
	s_waitcnt lgkmcnt(14)
	ds_read_b128 v[222:225], v218 offset:18016
	v_permlane32_swap_b32_e32 v124, v125
	v_max_f32_e32 v126, v124, v125
	v_lshl_add_u64 v[244:245], v[244:245], 0, s[46:47]
	v_lshl_add_u64 v[248:249], v[248:249], 0, s[46:47]
	v_lshl_add_u64 v[250:251], v[250:251], 0, s[48:49]
	s_add_i32 s10, s10, 2
	s_add_i32 s12, s10, 2
	s_cmp_ge_i32 s12, s35
	s_cbranch_scc0 .Lfox_loop
	s_waitcnt vmcnt(0) lgkmcnt(0)
	s_setprio 0
	s_branch .LBB0_670

.Lmla_nokrp:
	s_or_b64 exec, exec, s[4:5]
	global_load_dwordx4 v[130:133], v227, s[54:55]
	s_add_u32 s54, s54, 0x10000
	s_addc_u32 s55, s55, 0
	s_add_u32 s56, s56, 0x1000
	s_addc_u32 s57, s57, 0
	ds_read_b128 v[134:137], v162 offset:13312
	ds_read_b128 v[138:141], v162 offset:19968
	ds_read_b128 v[142:145], v162 offset:13344
	ds_read_b128 v[168:171], v162 offset:20000
	ds_read_b128 v[172:175], v162 offset:13376
	ds_read_b128 v[178:181], v162 offset:20032
	ds_read_b128 v[182:185], v162 offset:13408
	ds_read_b128 v[186:189], v162 offset:20064
	ds_read_b128 v[206:209], v162 offset:13440
	ds_read_b128 v[210:213], v162 offset:20096
	ds_read_b128 v[214:217], v162 offset:13472
	ds_read_b128 v[248:251], v162 offset:20128
	v_max3_f32 v240, v46, v47, v48
	v_max3_f32 v241, v49, v50, v51
	v_max3_f32 v240, v240, v52, v53
	v_max3_f32 v241, v241, v54, v55
	v_max3_f32 v240, v240, v56, v57
	v_max3_f32 v241, v241, v58, v59
	v_max3_f32 v240, v240, v60, v61
	v_max3_f32 v241, v241, v62, v63
	v_max3_f32 v240, v240, v64, v65
	v_max3_f32 v241, v241, v66, v67
	v_max3_f32 v240, v240, v68, v69
	v_max3_f32 v241, v241, v70, v71
	v_max3_f32 v240, v240, v72, v73
	v_max3_f32 v241, v241, v74, v75
	v_max3_f32 v240, v240, v76, v77
	v_max_f32_e32 v240, v240, v241
	v_mov_b32_e32 v241, v240
	s_nop 1
	v_permlane32_swap_b32_e32 v240, v241
	v_max_f32_e32 v244, v240, v241
	v_mov_b32_e32 v164, v244
	v_sub_f32_e32 v190, 0, v244
	v_mov_b32_e32 v191, v190
	v_mov_b32_e32 v192, v190
	v_mov_b32_e32 v193, v190
	v_mov_b32_e32 v194, v190
	v_mov_b32_e32 v195, v190
	v_mov_b32_e32 v196, v190
	v_mov_b32_e32 v197, v190
	v_mov_b32_e32 v198, v190
	v_mov_b32_e32 v199, v190
	v_mov_b32_e32 v200, v190
	v_mov_b32_e32 v201, v190
	v_mov_b32_e32 v202, v190
	v_mov_b32_e32 v203, v190
	v_mov_b32_e32 v204, v190
	v_mov_b32_e32 v205, v190
	v_sub_f32_e32 v46, v46, v164
	v_sub_f32_e32 v47, v47, v164
	v_sub_f32_e32 v48, v48, v164
	v_sub_f32_e32 v49, v49, v164
	v_sub_f32_e32 v50, v50, v164
	v_sub_f32_e32 v51, v51, v164
	v_sub_f32_e32 v52, v52, v164
	v_sub_f32_e32 v53, v53, v164
	v_sub_f32_e32 v54, v54, v164
	v_sub_f32_e32 v55, v55, v164
	v_sub_f32_e32 v56, v56, v164
	v_sub_f32_e32 v57, v57, v164
	v_sub_f32_e32 v58, v58, v164
	v_sub_f32_e32 v59, v59, v164
	v_sub_f32_e32 v60, v60, v164
	v_sub_f32_e32 v61, v61, v164
	v_sub_f32_e32 v62, v62, v164
	v_sub_f32_e32 v63, v63, v164
	v_sub_f32_e32 v64, v64, v164
	v_sub_f32_e32 v65, v65, v164
	v_sub_f32_e32 v66, v66, v164
	v_sub_f32_e32 v67, v67, v164
	v_sub_f32_e32 v68, v68, v164
	v_sub_f32_e32 v69, v69, v164
	v_sub_f32_e32 v70, v70, v164
	v_sub_f32_e32 v71, v71, v164
	v_sub_f32_e32 v72, v72, v164
	v_sub_f32_e32 v73, v73, v164
	v_sub_f32_e32 v74, v74, v164
	v_sub_f32_e32 v75, v75, v164
	v_sub_f32_e32 v76, v76, v164
	v_sub_f32_e32 v77, v77, v164
	v_mov_b32_e32 v244, 0
	s_mov_b32 s10, 6
	s_cmp_ge_u32 s33, 4
	s_cbranch_scc0 .Lnoprio_m
	s_setprio 1
.Lnoprio_m:
.Lmla_loop:
	v_cmp_lt_f32_e32 vcc, 0x41800000, v244
	s_cbranch_vccnz .Lmla_resc0

.Lmla_nokr1:
	s_or_b64 exec, exec, s[4:5]
	v_add_f32_e32 v242, v242, v104
	v_add_f32_e32 v243, v243, v105
	v_add_f32_e32 v238, v238, v106
	v_add_f32_e32 v239, v239, v107
	v_add_f32_e32 v242, v242, v108
	v_add_f32_e32 v243, v243, v109
	v_add_f32_e32 v238, v238, v239
	v_mfma_f32_32x32x16_bf16 v[14:29], v[172:175], v[230:233], v[14:29]
	ds_read_b128 v[172:175], v162 offset:13376
	v_add_f32_e32 v242, v242, v243
	v_add_f32_e32 v238, v238, v242
	v_add_f32_e32 v165, v165, v238
	v_max3_f32 v240, v46, v47, v48
	v_max3_f32 v241, v49, v50, v51
	v_max3_f32 v240, v240, v52, v53
	v_mfma_f32_32x32x16_bf16 v[30:45], v[178:181], v[230:233], v[30:45]
	ds_read_b128 v[178:181], v162 offset:20032
	global_load_dwordx4 v[130:133], v227, s[54:55]
	s_add_u32 s54, s54, 0x10000
	s_addc_u32 s55, s55, 0
	s_add_u32 s56, s56, 0x1000
	s_addc_u32 s57, s57, 0
	v_max3_f32 v241, v241, v54, v55
	v_max3_f32 v240, v240, v56, v57
	v_max3_f32 v241, v241, v58, v59
	v_max3_f32 v240, v240, v60, v61
	v_max3_f32 v241, v241, v62, v63
	v_max3_f32 v240, v240, v64, v65
	v_mfma_f32_32x32x16_bf16 v[14:29], v[182:185], v[234:237], v[14:29]
	ds_read_b128 v[182:185], v162 offset:13408
	v_max3_f32 v241, v241, v66, v67
	v_max3_f32 v240, v240, v68, v69
	v_max3_f32 v241, v241, v70, v71
	v_max3_f32 v240, v240, v72, v73
	v_max3_f32 v241, v241, v74, v75
	v_mfma_f32_32x32x16_bf16 v[30:45], v[186:189], v[234:237], v[30:45]
	ds_read_b128 v[186:189], v162 offset:20064
	v_max3_f32 v240, v240, v76, v77
	v_max_f32_e32 v240, v240, v241
	v_mov_b32_e32 v241, v240
	s_nop 1
	v_permlane32_swap_b32_e32 v240, v241
	v_max_f32_e32 v244, v240, v241
	s_add_i32 s10, s10, 2
	s_add_i32 s4, s35, 2
	s_cmp_ge_u32 s10, s4
	s_cbranch_scc0 .Lmla_loop
	s_waitcnt vmcnt(0) lgkmcnt(0)
	v_add_f32_e32 v46, v46, v164
	v_add_f32_e32 v47, v47, v164
	v_add_f32_e32 v48, v48, v164
	v_add_f32_e32 v49, v49, v164
	v_add_f32_e32 v50, v50, v164
	v_add_f32_e32 v51, v51, v164
	v_add_f32_e32 v52, v52, v164
	v_add_f32_e32 v53, v53, v164
	v_add_f32_e32 v54, v54, v164
	v_add_f32_e32 v55, v55, v164
	v_add_f32_e32 v56, v56, v164
	v_add_f32_e32 v57, v57, v164
	v_add_f32_e32 v58, v58, v164
	v_add_f32_e32 v59, v59, v164
	v_add_f32_e32 v60, v60, v164
	v_add_f32_e32 v61, v61, v164
	v_add_f32_e32 v62, v62, v164
	v_add_f32_e32 v63, v63, v164
	v_add_f32_e32 v64, v64, v164
	v_add_f32_e32 v65, v65, v164
	v_add_f32_e32 v66, v66, v164
	v_add_f32_e32 v67, v67, v164
	v_add_f32_e32 v68, v68, v164
	v_add_f32_e32 v69, v69, v164
	v_add_f32_e32 v70, v70, v164
	v_add_f32_e32 v71, v71, v164
	v_add_f32_e32 v72, v72, v164
	v_add_f32_e32 v73, v73, v164
	v_add_f32_e32 v74, v74, v164
	v_add_f32_e32 v75, v75, v164
	v_add_f32_e32 v76, v76, v164
	v_add_f32_e32 v77, v77, v164
	s_setprio 0
	s_branch .LBB0_738
